# scan forward direction: first half step's y reduction deferred into the next half step's sk reduction rounds (4 interleaved DPP chains), on top of hazard-slot fill and pinned placement
# speedup vs baseline: 1.0039x; 1.0039x over previous
; DI void scan_item(const Params& p, int l, bool ctx_out, int item, char* smem) {
;     ...
;     for (int i = 0; i < TC; ++i) {
;       const f32x4 w4 = nw4, kk4 = nkk4, b4 = nb4, k4 = nk4, r4 = nr4, v4 = nv4;
;       if (i + 1 < TC) {
;         const int i1 = i + 1;
;         nw4 = *(const f32x4*)(ops + (i1 * 4 + 0) * 64 + 4 * kg);
;         nkk4 = *(const f32x4*)(ops + (i1 * 4 + 1) * 64 + 4 * kg);
;         nb4 = *(const f32x4*)(ops + (i1 * 4 + 2) * 64 + 4 * kg);
;         nk4 = *(const f32x4*)(ops + (i1 * 4 + 3) * 64 + 4 * kg);
;         nr4 = *(const f32x4*)(zs + (i1 * 3 + 0) * 64 + 4 * kg);
;         nv4 = *(const f32x4*)(zs + (i1 * 3 + 2) * 64 + 16 * w + 4 * rg);
;       }
;       float sk[4], y[4];
; #pragma unroll
;       for (int a = 0; a < 4; ++a) {
;         sk[a] = S[a][0] * kk4[0] + S[a][1] * kk4[1] + S[a][2] * kk4[2] + S[a][3] * kk4[3];
;         if (dir == 1) y[a] = S[a][0] * r4[0] + S[a][1] * r4[1] + S[a][2] * r4[2] + S[a][3] * r4[3];
;       }
; #pragma unroll
;       for (int a = 0; a < 4; ++a) sk[a] = allred16(sk[a]);
; #pragma unroll
;       for (int a = 0; a < 4; ++a)
; #pragma unroll
;         for (int j = 0; j < 4; ++j) S[a][j] = S[a][j] * w4[j] + (v4[a] * k4[j] - sk[a] * b4[j]);
;       if (dir == 0) {
; #pragma unroll
;         for (int a = 0; a < 4; ++a) y[a] = S[a][0] * r4[0] + S[a][1] * r4[1] + S[a][2] * r4[2] + S[a][3] * r4[3];
;       }
.Lscan_step_loop0:
	ds_read_b128 v[96:99], v249 offset:2560
	ds_read_b128 v[100:103], v249 offset:2576
	ds_read_b128 v[80:83], v249 offset:2048
	ds_read_b128 v[84:87], v249 offset:2064
	ds_read_b64 v[104:105], v250 offset:1536
	s_waitcnt lgkmcnt(9)
	s_add_i32 s53, s53, 1
	v_pk_mul_f32 v[122:123], v[6:7], v[30:31] op_sel_hi:[1,0]
	v_pk_mul_f32 v[126:127], v[8:9], v[30:31] op_sel:[0,1] op_sel_hi:[1,1]
	v_pk_fma_f32 v[122:123], v[10:11], v[32:33], v[122:123] op_sel_hi:[1,0,1]
	v_pk_fma_f32 v[126:127], v[12:13], v[32:33], v[126:127] op_sel:[0,1,0] op_sel_hi:[1,1,1]
	v_pk_fma_f32 v[122:123], v[14:15], v[34:35], v[122:123] op_sel_hi:[1,0,1]
	v_pk_fma_f32 v[126:127], v[16:17], v[34:35], v[126:127] op_sel:[0,1,0] op_sel_hi:[1,1,1]
	v_pk_fma_f32 v[122:123], v[18:19], v[36:37], v[122:123] op_sel_hi:[1,0,1]
	v_pk_fma_f32 v[126:127], v[20:21], v[36:37], v[126:127] op_sel:[0,1,0] op_sel_hi:[1,1,1]
	v_pk_add_f32 v[122:123], v[122:123], v[126:127]
	v_pk_fma_f32 v[6:7], v[62:63], v[46:47], v[6:7] op_sel_hi:[1,0,1]
	v_pk_fma_f32 v[8:9], v[62:63], v[46:47], v[8:9] op_sel:[0,1,0] op_sel_hi:[1,1,1]
	v_add_f32_dpp v122, v122, v122 quad_perm:[1,0,3,2] row_mask:0xf bank_mask:0xf bound_ctrl:1
	v_add_f32_dpp v123, v123, v123 quad_perm:[1,0,3,2] row_mask:0xf bank_mask:0xf bound_ctrl:1
	v_pk_fma_f32 v[10:11], v[62:63], v[48:49], v[10:11] op_sel_hi:[1,0,1]
	v_add_f32_dpp v122, v122, v122 quad_perm:[2,3,0,1] row_mask:0xf bank_mask:0xf bound_ctrl:1
	v_add_f32_dpp v123, v123, v123 quad_perm:[2,3,0,1] row_mask:0xf bank_mask:0xf bound_ctrl:1
	v_pk_fma_f32 v[12:13], v[62:63], v[48:49], v[12:13] op_sel:[0,1,0] op_sel_hi:[1,1,1]
	v_add_f32_dpp v122, v122, v122 row_half_mirror row_mask:0xf bank_mask:0xf bound_ctrl:1
	v_add_f32_dpp v123, v123, v123 row_half_mirror row_mask:0xf bank_mask:0xf bound_ctrl:1
	v_pk_fma_f32 v[14:15], v[62:63], v[50:51], v[14:15] op_sel_hi:[1,0,1]
	v_pk_fma_f32 v[16:17], v[62:63], v[50:51], v[16:17] op_sel:[0,1,0] op_sel_hi:[1,1,1]
	v_pk_fma_f32 v[18:19], v[62:63], v[52:53], v[18:19] op_sel_hi:[1,0,1]
	v_pk_fma_f32 v[20:21], v[62:63], v[52:53], v[20:21] op_sel:[0,1,0] op_sel_hi:[1,1,1]
	v_pk_fma_f32 v[6:7], v[122:123], v[38:39], v[6:7] op_sel_hi:[1,0,1] neg_lo:[1,0,0] neg_hi:[1,0,0]
	v_pk_fma_f32 v[8:9], v[122:123], v[38:39], v[8:9] op_sel:[0,1,0] op_sel_hi:[1,1,1] neg_lo:[1,0,0] neg_hi:[1,0,0]
	v_pk_mul_f32 v[124:125], v[6:7], v[54:55] op_sel_hi:[1,0]
	v_pk_fma_f32 v[10:11], v[122:123], v[40:41], v[10:11] op_sel_hi:[1,0,1] neg_lo:[1,0,0] neg_hi:[1,0,0]
	v_pk_mul_f32 v[128:129], v[8:9], v[54:55] op_sel:[0,1] op_sel_hi:[1,1]
	v_pk_fma_f32 v[12:13], v[122:123], v[40:41], v[12:13] op_sel:[0,1,0] op_sel_hi:[1,1,1] neg_lo:[1,0,0] neg_hi:[1,0,0]
	v_pk_fma_f32 v[124:125], v[10:11], v[56:57], v[124:125] op_sel_hi:[1,0,1]
	v_pk_fma_f32 v[14:15], v[122:123], v[42:43], v[14:15] op_sel_hi:[1,0,1] neg_lo:[1,0,0] neg_hi:[1,0,0]
	v_pk_fma_f32 v[128:129], v[12:13], v[56:57], v[128:129] op_sel:[0,1,0] op_sel_hi:[1,1,1]
	v_pk_fma_f32 v[16:17], v[122:123], v[42:43], v[16:17] op_sel:[0,1,0] op_sel_hi:[1,1,1] neg_lo:[1,0,0] neg_hi:[1,0,0]
	v_pk_fma_f32 v[124:125], v[14:15], v[58:59], v[124:125] op_sel_hi:[1,0,1]
	v_pk_fma_f32 v[18:19], v[122:123], v[44:45], v[18:19] op_sel_hi:[1,0,1] neg_lo:[1,0,0] neg_hi:[1,0,0]
	v_pk_fma_f32 v[128:129], v[16:17], v[58:59], v[128:129] op_sel:[0,1,0] op_sel_hi:[1,1,1]
	v_pk_fma_f32 v[20:21], v[122:123], v[44:45], v[20:21] op_sel:[0,1,0] op_sel_hi:[1,1,1] neg_lo:[1,0,0] neg_hi:[1,0,0]
	v_pk_fma_f32 v[124:125], v[18:19], v[60:61], v[124:125] op_sel_hi:[1,0,1]
	v_pk_fma_f32 v[128:129], v[20:21], v[60:61], v[128:129] op_sel:[0,1,0] op_sel_hi:[1,1,1]
	v_pk_add_f32 v[124:125], v[124:125], v[128:129]
	ds_read_b128 v[30:33], v249 offset:3328
	ds_read_b128 v[34:37], v249 offset:3344
	ds_read_b128 v[46:49], v249 offset:3840
	ds_read_b128 v[50:53], v249 offset:3856
	ds_read_b128 v[54:57], v249 offset:4096
	ds_read_b128 v[58:61], v249 offset:4112
	ds_read_b128 v[38:41], v249 offset:3584
	ds_read_b128 v[42:45], v249 offset:3600
	ds_read_b64 v[62:63], v250 offset:3072
	s_waitcnt lgkmcnt(9)
; DI unsigned pack2(float a, float b) { f32x2_t v = {a, b}; bf16x2_t r = __builtin_convertvector(v, bf16x2_t); return __builtin_bit_cast(unsigned, r); }
; DI void scan_item(const Params& p, int l, bool ctx_out, int item, char* smem) {
;     ...
;       float sk[4], y[4];
; #pragma unroll
;       for (int a = 0; a < 4; ++a) {
;         sk[a] = S[a][0] * kk4[0] + S[a][1] * kk4[1] + S[a][2] * kk4[2] + S[a][3] * kk4[3];
;         if (dir == 1) y[a] = S[a][0] * r4[0] + S[a][1] * r4[1] + S[a][2] * r4[2] + S[a][3] * r4[3];
;       }
; #pragma unroll
;       for (int a = 0; a < 4; ++a) sk[a] = allred16(sk[a]);
; #pragma unroll
;       for (int a = 0; a < 4; ++a)
; #pragma unroll
;         for (int j = 0; j < 4; ++j) S[a][j] = S[a][j] * w4[j] + (v4[a] * k4[j] - sk[a] * b4[j]);
;       if (dir == 0) {
; #pragma unroll
;         for (int a = 0; a < 4; ++a) y[a] = S[a][0] * r4[0] + S[a][1] * r4[1] + S[a][2] * r4[2] + S[a][3] * r4[3];
;       }
;       if (emit) {
;         float bo = r4[0] * k4[0] * rk4[0] + r4[1] * k4[1] * rk4[1] + r4[2] * k4[2] * rk4[2] + r4[3] * k4[3] * rk4[3];
;         bo = allred16(bo);
; #pragma unroll
;         for (int a = 0; a < 4; ++a) y[a] = allred16(y[a]);
;         if (kg == 0) {
;           const int sidx = c0 + i;
;           const int row = rbase + (dir == 0 ? sidx : n - 1 - sidx);
;           *(u32x2*)(YD + (size_t)row * 512 + h * 64 + 16 * w + 4 * rg) = mk2(pack2(y[0], y[1]), pack2(y[2], y[3]));
	s_cmp_lt_u32 s53, 8
	v_pk_mul_f32 v[122:123], v[6:7], v[72:73] op_sel_hi:[1,0]
	v_pk_mul_f32 v[126:127], v[8:9], v[72:73] op_sel:[0,1] op_sel_hi:[1,1]
	v_pk_fma_f32 v[122:123], v[10:11], v[74:75], v[122:123] op_sel_hi:[1,0,1]
	v_pk_fma_f32 v[126:127], v[12:13], v[74:75], v[126:127] op_sel:[0,1,0] op_sel_hi:[1,1,1]
	v_pk_fma_f32 v[122:123], v[14:15], v[76:77], v[122:123] op_sel_hi:[1,0,1]
	v_pk_fma_f32 v[126:127], v[16:17], v[76:77], v[126:127] op_sel:[0,1,0] op_sel_hi:[1,1,1]
	v_pk_fma_f32 v[122:123], v[18:19], v[78:79], v[122:123] op_sel_hi:[1,0,1]
	v_pk_fma_f32 v[126:127], v[20:21], v[78:79], v[126:127] op_sel:[0,1,0] op_sel_hi:[1,1,1]
	v_pk_add_f32 v[122:123], v[122:123], v[126:127]
	v_pk_fma_f32 v[6:7], v[104:105], v[88:89], v[6:7] op_sel_hi:[1,0,1]
	v_pk_fma_f32 v[8:9], v[104:105], v[88:89], v[8:9] op_sel:[0,1,0] op_sel_hi:[1,1,1]
	v_add_f32_dpp v122, v122, v122 quad_perm:[1,0,3,2] row_mask:0xf bank_mask:0xf bound_ctrl:1
	v_add_f32_dpp v123, v123, v123 quad_perm:[1,0,3,2] row_mask:0xf bank_mask:0xf bound_ctrl:1
	v_add_f32_dpp v124, v124, v124 quad_perm:[1,0,3,2] row_mask:0xf bank_mask:0xf bound_ctrl:1
	v_add_f32_dpp v125, v125, v125 quad_perm:[1,0,3,2] row_mask:0xf bank_mask:0xf bound_ctrl:1
	v_add_f32_dpp v122, v122, v122 quad_perm:[2,3,0,1] row_mask:0xf bank_mask:0xf bound_ctrl:1
	v_add_f32_dpp v123, v123, v123 quad_perm:[2,3,0,1] row_mask:0xf bank_mask:0xf bound_ctrl:1
	v_add_f32_dpp v124, v124, v124 quad_perm:[2,3,0,1] row_mask:0xf bank_mask:0xf bound_ctrl:1
	v_add_f32_dpp v125, v125, v125 quad_perm:[2,3,0,1] row_mask:0xf bank_mask:0xf bound_ctrl:1
	v_add_f32_dpp v122, v122, v122 row_half_mirror row_mask:0xf bank_mask:0xf bound_ctrl:1
	v_add_f32_dpp v123, v123, v123 row_half_mirror row_mask:0xf bank_mask:0xf bound_ctrl:1
	v_add_f32_dpp v124, v124, v124 row_half_mirror row_mask:0xf bank_mask:0xf bound_ctrl:1
	v_add_f32_dpp v125, v125, v125 row_half_mirror row_mask:0xf bank_mask:0xf bound_ctrl:1
	v_cvt_pk_bf16_f32 v247, v124, v125
	ds_write_b32 v251, v247 offset:0
	v_pk_fma_f32 v[10:11], v[104:105], v[90:91], v[10:11] op_sel_hi:[1,0,1]
	v_pk_fma_f32 v[12:13], v[104:105], v[90:91], v[12:13] op_sel:[0,1,0] op_sel_hi:[1,1,1]
	v_pk_fma_f32 v[14:15], v[104:105], v[92:93], v[14:15] op_sel_hi:[1,0,1]
	v_pk_fma_f32 v[16:17], v[104:105], v[92:93], v[16:17] op_sel:[0,1,0] op_sel_hi:[1,1,1]
	v_pk_fma_f32 v[18:19], v[104:105], v[94:95], v[18:19] op_sel_hi:[1,0,1]
	v_pk_fma_f32 v[20:21], v[104:105], v[94:95], v[20:21] op_sel:[0,1,0] op_sel_hi:[1,1,1]
	v_pk_fma_f32 v[6:7], v[122:123], v[80:81], v[6:7] op_sel_hi:[1,0,1] neg_lo:[1,0,0] neg_hi:[1,0,0]
	v_pk_fma_f32 v[8:9], v[122:123], v[80:81], v[8:9] op_sel:[0,1,0] op_sel_hi:[1,1,1] neg_lo:[1,0,0] neg_hi:[1,0,0]
	v_pk_mul_f32 v[124:125], v[6:7], v[96:97] op_sel_hi:[1,0]
	v_pk_fma_f32 v[10:11], v[122:123], v[82:83], v[10:11] op_sel_hi:[1,0,1] neg_lo:[1,0,0] neg_hi:[1,0,0]
	v_pk_mul_f32 v[128:129], v[8:9], v[96:97] op_sel:[0,1] op_sel_hi:[1,1]
	v_pk_fma_f32 v[12:13], v[122:123], v[82:83], v[12:13] op_sel:[0,1,0] op_sel_hi:[1,1,1] neg_lo:[1,0,0] neg_hi:[1,0,0]
	v_pk_fma_f32 v[124:125], v[10:11], v[98:99], v[124:125] op_sel_hi:[1,0,1]
	v_pk_fma_f32 v[14:15], v[122:123], v[84:85], v[14:15] op_sel_hi:[1,0,1] neg_lo:[1,0,0] neg_hi:[1,0,0]
	v_pk_fma_f32 v[128:129], v[12:13], v[98:99], v[128:129] op_sel:[0,1,0] op_sel_hi:[1,1,1]
	v_pk_fma_f32 v[16:17], v[122:123], v[84:85], v[16:17] op_sel:[0,1,0] op_sel_hi:[1,1,1] neg_lo:[1,0,0] neg_hi:[1,0,0]
	v_pk_fma_f32 v[124:125], v[14:15], v[100:101], v[124:125] op_sel_hi:[1,0,1]
	v_pk_fma_f32 v[18:19], v[122:123], v[86:87], v[18:19] op_sel_hi:[1,0,1] neg_lo:[1,0,0] neg_hi:[1,0,0]
	v_pk_fma_f32 v[128:129], v[16:17], v[100:101], v[128:129] op_sel:[0,1,0] op_sel_hi:[1,1,1]
	v_pk_fma_f32 v[20:21], v[122:123], v[86:87], v[20:21] op_sel:[0,1,0] op_sel_hi:[1,1,1] neg_lo:[1,0,0] neg_hi:[1,0,0]
	v_pk_fma_f32 v[124:125], v[18:19], v[102:103], v[124:125] op_sel_hi:[1,0,1]
	v_pk_fma_f32 v[128:129], v[20:21], v[102:103], v[128:129] op_sel:[0,1,0] op_sel_hi:[1,1,1]
	v_pk_add_f32 v[124:125], v[124:125], v[128:129]
	ds_read_b128 v[72:75], v249 offset:4864
	ds_read_b128 v[76:79], v249 offset:4880
	v_add_f32_dpp v124, v124, v124 quad_perm:[1,0,3,2] row_mask:0xf bank_mask:0xf bound_ctrl:1
	v_add_f32_dpp v125, v125, v125 quad_perm:[1,0,3,2] row_mask:0xf bank_mask:0xf bound_ctrl:1
	ds_read_b128 v[88:91], v249 offset:5376
	v_add_f32_dpp v124, v124, v124 quad_perm:[2,3,0,1] row_mask:0xf bank_mask:0xf bound_ctrl:1
	v_add_f32_dpp v125, v125, v125 quad_perm:[2,3,0,1] row_mask:0xf bank_mask:0xf bound_ctrl:1
	ds_read_b128 v[92:95], v249 offset:5392
	v_add_f32_dpp v124, v124, v124 row_half_mirror row_mask:0xf bank_mask:0xf bound_ctrl:1
	v_add_f32_dpp v125, v125, v125 row_half_mirror row_mask:0xf bank_mask:0xf bound_ctrl:1
	v_cvt_pk_bf16_f32 v247, v124, v125
	ds_write_b32 v251, v247 offset:128
	v_add_u32_e32 v249, 3072, v249
	v_add_u32_e32 v250, 3072, v250
	v_add_u32_e32 v251, 256, v251
	s_cbranch_scc1 .Lscan_step_loop0
	s_branch .Lscan_flush
	s_nop 0
	s_nop 0
	s_nop 0
	s_nop 0
	s_nop 0
	s_nop 0
	s_nop 0
	s_nop 0
	s_nop 0
	s_nop 0
	s_nop 0
	s_nop 0
	s_nop 0
	s_nop 0
	s_nop 0
